# in-proj/gate GEMM: the last tile of each workgroup stores write-through (sc1) so less dirty L2 data is left for the phase barrier's writeback
# speedup vs baseline: 1.0064x; 1.0016x over previous
.LBB0_337:
	v_cvt_pk_bf16_f32 v2, v10, v11
	v_cvt_pk_bf16_f32 v3, v12, v13
	v_cvt_pk_bf16_f32 v4, v14, v15
	v_cvt_pk_bf16_f32 v5, v16, v17
	s_and_b64 vcc, exec, s[6:7]
	s_mov_b32 s53, s47
	s_mov_b32 s54, s52
	s_mov_b64 s[24:25], s[10:11]
	s_mov_b64 s[22:23], s[8:9]
	s_cmp_lg_u64 s[6:7], 0
	s_cbranch_scc1 .Lwt_a1
	global_store_dwordx4 v[26:27], v[2:5], off offset:256 nt
	s_branch .Lwt_b1
.Lwt_a1:
	global_store_dwordx4 v[26:27], v[2:5], off offset:256 sc1 nt
.Lwt_b1:
	s_cbranch_vccnz .LBB0_410

.LBB0_349:
	v_lshl_add_u32 v178, s54, 8, v145
	v_lshl_or_b32 v156, s53, 8, v176
	v_mad_i64_i32 v[122:123], s[22:23], v178, s28, 0
	v_ashrrev_i32_e32 v157, 31, v156
	v_lshl_add_u64 v[122:123], v[122:123], 1, s[20:21]
	v_lshl_add_u64 v[158:159], v[156:157], 1, v[122:123]
	v_cvt_pk_bf16_f32 v122, v130, v131
	v_cvt_pk_bf16_f32 v123, v132, v133
	v_cvt_pk_bf16_f32 v124, v134, v135
	v_cvt_pk_bf16_f32 v125, v136, v137
	s_and_b64 vcc, exec, s[14:15]
	s_cmp_lg_u64 s[6:7], 0
	s_cbranch_scc1 .Lwt_a2
	global_store_dwordx4 v[158:159], v[122:125], off nt
	s_branch .Lwt_b2
.Lwt_a2:
	global_store_dwordx4 v[158:159], v[122:125], off sc1 nt
.Lwt_b2:
	s_cbranch_vccz .LBB0_394
	s_nop 0
	v_mul_f32_e32 v123, 0xbfb8aa3b, v114
	v_exp_f32_e32 v123, v123
	v_mul_f32_e32 v124, 0xbfb8aa3b, v119
	v_mul_f32_e32 v125, 0xbfb8aa3b, v115
	v_exp_f32_e32 v124, v124
	v_exp_f32_e32 v125, v125
	v_add_f32_e32 v123, 1.0, v123
	v_rcp_f32_e32 v126, v123
	v_add_f32_e32 v123, 1.0, v124
	v_add_f32_e32 v124, 1.0, v125
	v_mul_f32_e32 v125, 0xbfb8aa3b, v120
	v_mul_f32_e32 v127, 0xbfb8aa3b, v116
	v_exp_f32_e32 v125, v125
	v_exp_f32_e32 v128, v127
	v_rcp_f32_e32 v127, v124
	v_mul_f32_e32 v122, 0xbfb8aa3b, v118
	v_add_f32_e32 v124, 1.0, v125
	v_add_f32_e32 v125, 1.0, v128
	v_mul_f32_e32 v128, 0xbfb8aa3b, v121
	v_exp_f32_e32 v129, v128
	v_mul_f32_e32 v128, 0xbfb8aa3b, v117
	v_exp_f32_e32 v122, v122
	v_exp_f32_e32 v130, v128
	v_rcp_f32_e32 v128, v125
	v_add_f32_e32 v125, 1.0, v129
	v_add_f32_e32 v122, 1.0, v122
	v_add_f32_e32 v129, 1.0, v130
	v_rcp_f32_e32 v122, v122
	v_rcp_f32_e32 v123, v123
	v_rcp_f32_e32 v124, v124
	v_rcp_f32_e32 v125, v125
	v_rcp_f32_e32 v129, v129
	s_cbranch_execnz .LBB0_352

.LBB0_352:
	v_cvt_pk_bf16_f32 v114, v122, v123
	v_cvt_pk_bf16_f32 v115, v124, v125
	v_cvt_pk_bf16_f32 v116, v126, v127
	v_cvt_pk_bf16_f32 v117, v128, v129
	s_and_b64 vcc, exec, s[14:15]
	s_cmp_lg_u64 s[6:7], 0
	s_cbranch_scc1 .Lwt_a3
	global_store_dwordx4 v[158:159], v[114:117], off offset:256 nt
	s_branch .Lwt_b3
.Lwt_a3:
	global_store_dwordx4 v[158:159], v[114:117], off offset:256 sc1 nt
.Lwt_b3:
	s_cbranch_vccz .LBB0_395
	s_nop 0
	v_mul_f32_e32 v115, 0xbfb8aa3b, v106
	v_exp_f32_e32 v115, v115
	v_mul_f32_e32 v116, 0xbfb8aa3b, v111
	v_mul_f32_e32 v117, 0xbfb8aa3b, v107
	v_exp_f32_e32 v116, v116
	v_exp_f32_e32 v117, v117
	v_add_f32_e32 v115, 1.0, v115
	v_rcp_f32_e32 v118, v115
	v_add_f32_e32 v115, 1.0, v116
	v_add_f32_e32 v116, 1.0, v117
	v_mul_f32_e32 v117, 0xbfb8aa3b, v112
	v_mul_f32_e32 v119, 0xbfb8aa3b, v108
	v_exp_f32_e32 v117, v117
	v_exp_f32_e32 v120, v119
	v_rcp_f32_e32 v119, v116
	v_mul_f32_e32 v114, 0xbfb8aa3b, v110
	v_add_f32_e32 v116, 1.0, v117
	v_add_f32_e32 v117, 1.0, v120
	v_mul_f32_e32 v120, 0xbfb8aa3b, v113
	v_exp_f32_e32 v121, v120
	v_mul_f32_e32 v120, 0xbfb8aa3b, v109
	v_exp_f32_e32 v114, v114
	v_exp_f32_e32 v122, v120
	v_rcp_f32_e32 v120, v117
	v_add_f32_e32 v117, 1.0, v121
	v_add_f32_e32 v114, 1.0, v114
	v_add_f32_e32 v121, 1.0, v122
	v_rcp_f32_e32 v114, v114
	v_rcp_f32_e32 v115, v115
	v_rcp_f32_e32 v116, v116
	v_rcp_f32_e32 v117, v117
	v_rcp_f32_e32 v121, v121
	s_cbranch_execnz .LBB0_355

.LBB0_355:
	v_or_b32_e32 v106, 16, v178
	v_mad_i64_i32 v[106:107], s[22:23], v106, s28, 0
	v_lshl_add_u64 v[106:107], v[106:107], 1, s[20:21]
	v_lshl_add_u64 v[122:123], v[156:157], 1, v[106:107]
	v_cvt_pk_bf16_f32 v106, v114, v115
	v_cvt_pk_bf16_f32 v107, v116, v117
	v_cvt_pk_bf16_f32 v108, v118, v119
	v_cvt_pk_bf16_f32 v109, v120, v121
	s_and_b64 vcc, exec, s[14:15]
	s_cmp_lg_u64 s[6:7], 0
	s_cbranch_scc1 .Lwt_a4
	global_store_dwordx4 v[122:123], v[106:109], off nt
	s_branch .Lwt_b4
.Lwt_a4:
	global_store_dwordx4 v[122:123], v[106:109], off sc1 nt
.Lwt_b4:
	s_cbranch_vccz .LBB0_396
	s_nop 0
	v_mul_f32_e32 v107, 0xbfb8aa3b, v98
	v_exp_f32_e32 v107, v107
	v_mul_f32_e32 v108, 0xbfb8aa3b, v103
	v_mul_f32_e32 v109, 0xbfb8aa3b, v99
	v_exp_f32_e32 v108, v108
	v_exp_f32_e32 v109, v109
	v_add_f32_e32 v107, 1.0, v107
	v_rcp_f32_e32 v110, v107
	v_add_f32_e32 v107, 1.0, v108
	v_add_f32_e32 v108, 1.0, v109
	v_mul_f32_e32 v109, 0xbfb8aa3b, v104
	v_mul_f32_e32 v111, 0xbfb8aa3b, v100
	v_exp_f32_e32 v109, v109
	v_exp_f32_e32 v112, v111
	v_rcp_f32_e32 v111, v108
	v_mul_f32_e32 v106, 0xbfb8aa3b, v102
	v_add_f32_e32 v108, 1.0, v109
	v_add_f32_e32 v109, 1.0, v112
	v_mul_f32_e32 v112, 0xbfb8aa3b, v105
	v_exp_f32_e32 v113, v112
	v_mul_f32_e32 v112, 0xbfb8aa3b, v101
	v_exp_f32_e32 v106, v106
	v_exp_f32_e32 v114, v112
	v_rcp_f32_e32 v112, v109
	v_add_f32_e32 v109, 1.0, v113
	v_add_f32_e32 v106, 1.0, v106
	v_add_f32_e32 v113, 1.0, v114
	v_rcp_f32_e32 v106, v106
	v_rcp_f32_e32 v107, v107
	v_rcp_f32_e32 v108, v108
	v_rcp_f32_e32 v109, v109
	v_rcp_f32_e32 v113, v113
	s_cbranch_execnz .LBB0_358

.LBB0_358:
	v_cvt_pk_bf16_f32 v98, v106, v107
	v_cvt_pk_bf16_f32 v99, v108, v109
	v_cvt_pk_bf16_f32 v100, v110, v111
	v_cvt_pk_bf16_f32 v101, v112, v113
	s_and_b64 vcc, exec, s[14:15]
	s_cmp_lg_u64 s[6:7], 0
	s_cbranch_scc1 .Lwt_a5
	global_store_dwordx4 v[122:123], v[98:101], off offset:256 nt
	s_branch .Lwt_b5
.Lwt_a5:
	global_store_dwordx4 v[122:123], v[98:101], off offset:256 sc1 nt
.Lwt_b5:
	s_cbranch_vccz .LBB0_397
	s_nop 0
	v_mul_f32_e32 v99, 0xbfb8aa3b, v90
	v_exp_f32_e32 v99, v99
	v_mul_f32_e32 v100, 0xbfb8aa3b, v95
	v_mul_f32_e32 v101, 0xbfb8aa3b, v91
	v_exp_f32_e32 v100, v100
	v_exp_f32_e32 v101, v101
	v_add_f32_e32 v99, 1.0, v99
	v_rcp_f32_e32 v102, v99
	v_add_f32_e32 v99, 1.0, v100
	v_add_f32_e32 v100, 1.0, v101
	v_mul_f32_e32 v101, 0xbfb8aa3b, v96
	v_mul_f32_e32 v103, 0xbfb8aa3b, v92
	v_exp_f32_e32 v101, v101
	v_exp_f32_e32 v104, v103
	v_rcp_f32_e32 v103, v100
	v_mul_f32_e32 v98, 0xbfb8aa3b, v94
	v_add_f32_e32 v100, 1.0, v101
	v_add_f32_e32 v101, 1.0, v104
	v_mul_f32_e32 v104, 0xbfb8aa3b, v97
	v_exp_f32_e32 v105, v104
	v_mul_f32_e32 v104, 0xbfb8aa3b, v93
	v_exp_f32_e32 v98, v98
	v_exp_f32_e32 v106, v104
	v_rcp_f32_e32 v104, v101
	v_add_f32_e32 v101, 1.0, v105
	v_add_f32_e32 v98, 1.0, v98
	v_add_f32_e32 v105, 1.0, v106
	v_rcp_f32_e32 v98, v98
	v_rcp_f32_e32 v99, v99
	v_rcp_f32_e32 v100, v100
	v_rcp_f32_e32 v101, v101
	v_rcp_f32_e32 v105, v105
	s_cbranch_execnz .LBB0_361

.LBB0_361:
	v_or_b32_e32 v90, 32, v178
	v_mad_i64_i32 v[90:91], s[22:23], v90, s28, 0
	v_lshl_add_u64 v[90:91], v[90:91], 1, s[20:21]
	v_lshl_add_u64 v[106:107], v[156:157], 1, v[90:91]
	v_cvt_pk_bf16_f32 v90, v98, v99
	v_cvt_pk_bf16_f32 v91, v100, v101
	v_cvt_pk_bf16_f32 v92, v102, v103
	v_cvt_pk_bf16_f32 v93, v104, v105
	s_and_b64 vcc, exec, s[14:15]
	s_cmp_lg_u64 s[6:7], 0
	s_cbranch_scc1 .Lwt_a6
	global_store_dwordx4 v[106:107], v[90:93], off nt
	s_branch .Lwt_b6
.Lwt_a6:
	global_store_dwordx4 v[106:107], v[90:93], off sc1 nt
.Lwt_b6:
	s_cbranch_vccz .LBB0_398
	s_nop 0
	v_mul_f32_e32 v91, 0xbfb8aa3b, v82
	v_exp_f32_e32 v91, v91
	v_mul_f32_e32 v92, 0xbfb8aa3b, v87
	v_mul_f32_e32 v93, 0xbfb8aa3b, v83
	v_exp_f32_e32 v92, v92
	v_exp_f32_e32 v93, v93
	v_add_f32_e32 v91, 1.0, v91
	v_rcp_f32_e32 v94, v91
	v_add_f32_e32 v91, 1.0, v92
	v_add_f32_e32 v92, 1.0, v93
	v_mul_f32_e32 v93, 0xbfb8aa3b, v88
	v_mul_f32_e32 v95, 0xbfb8aa3b, v84
	v_exp_f32_e32 v93, v93
	v_exp_f32_e32 v96, v95
	v_rcp_f32_e32 v95, v92
	v_mul_f32_e32 v90, 0xbfb8aa3b, v86
	v_add_f32_e32 v92, 1.0, v93
	v_add_f32_e32 v93, 1.0, v96
	v_mul_f32_e32 v96, 0xbfb8aa3b, v89
	v_exp_f32_e32 v97, v96
	v_mul_f32_e32 v96, 0xbfb8aa3b, v85
	v_exp_f32_e32 v90, v90
	v_exp_f32_e32 v98, v96
	v_rcp_f32_e32 v96, v93
	v_add_f32_e32 v93, 1.0, v97
	v_add_f32_e32 v90, 1.0, v90
	v_add_f32_e32 v97, 1.0, v98
	v_rcp_f32_e32 v90, v90
	v_rcp_f32_e32 v91, v91
	v_rcp_f32_e32 v92, v92
	v_rcp_f32_e32 v93, v93
	v_rcp_f32_e32 v97, v97
	s_cbranch_execnz .LBB0_364

.LBB0_364:
	v_cvt_pk_bf16_f32 v82, v90, v91
	v_cvt_pk_bf16_f32 v83, v92, v93
	v_cvt_pk_bf16_f32 v84, v94, v95
	v_cvt_pk_bf16_f32 v85, v96, v97
	s_and_b64 vcc, exec, s[14:15]
	s_cmp_lg_u64 s[6:7], 0
	s_cbranch_scc1 .Lwt_a7
	global_store_dwordx4 v[106:107], v[82:85], off offset:256 nt
	s_branch .Lwt_b7
.Lwt_a7:
	global_store_dwordx4 v[106:107], v[82:85], off offset:256 sc1 nt
.Lwt_b7:
	s_cbranch_vccz .LBB0_399
	s_nop 0
	v_mul_f32_e32 v83, 0xbfb8aa3b, v74
	v_exp_f32_e32 v83, v83
	v_mul_f32_e32 v84, 0xbfb8aa3b, v79
	v_mul_f32_e32 v85, 0xbfb8aa3b, v75
	v_exp_f32_e32 v84, v84
	v_exp_f32_e32 v85, v85
	v_add_f32_e32 v83, 1.0, v83
	v_rcp_f32_e32 v86, v83
	v_add_f32_e32 v83, 1.0, v84
	v_add_f32_e32 v84, 1.0, v85
	v_mul_f32_e32 v85, 0xbfb8aa3b, v80
	v_mul_f32_e32 v87, 0xbfb8aa3b, v76
	v_exp_f32_e32 v85, v85
	v_exp_f32_e32 v88, v87
	v_rcp_f32_e32 v87, v84
	v_mul_f32_e32 v82, 0xbfb8aa3b, v78
	v_add_f32_e32 v84, 1.0, v85
	v_add_f32_e32 v85, 1.0, v88
	v_mul_f32_e32 v88, 0xbfb8aa3b, v81
	v_exp_f32_e32 v89, v88
	v_mul_f32_e32 v88, 0xbfb8aa3b, v77
	v_exp_f32_e32 v82, v82
	v_exp_f32_e32 v90, v88
	v_rcp_f32_e32 v88, v85
	v_add_f32_e32 v85, 1.0, v89
	v_add_f32_e32 v82, 1.0, v82
	v_add_f32_e32 v89, 1.0, v90
	v_rcp_f32_e32 v82, v82
	v_rcp_f32_e32 v83, v83
	v_rcp_f32_e32 v84, v84
	v_rcp_f32_e32 v85, v85
	v_rcp_f32_e32 v89, v89
	s_cbranch_execnz .LBB0_367

.LBB0_367:
	v_or_b32_e32 v74, 48, v178
	v_mad_i64_i32 v[74:75], s[22:23], v74, s28, 0
	v_lshl_add_u64 v[74:75], v[74:75], 1, s[20:21]
	v_lshl_add_u64 v[90:91], v[156:157], 1, v[74:75]
	v_cvt_pk_bf16_f32 v74, v82, v83
	v_cvt_pk_bf16_f32 v75, v84, v85
	v_cvt_pk_bf16_f32 v76, v86, v87
	v_cvt_pk_bf16_f32 v77, v88, v89
	s_and_b64 vcc, exec, s[14:15]
	s_cmp_lg_u64 s[6:7], 0
	s_cbranch_scc1 .Lwt_a8
	global_store_dwordx4 v[90:91], v[74:77], off nt
	s_branch .Lwt_b8
.Lwt_a8:
	global_store_dwordx4 v[90:91], v[74:77], off sc1 nt
.Lwt_b8:
	s_cbranch_vccz .LBB0_400
	s_nop 0
	v_mul_f32_e32 v75, 0xbfb8aa3b, v66
	v_exp_f32_e32 v75, v75
	v_mul_f32_e32 v76, 0xbfb8aa3b, v71
	v_mul_f32_e32 v77, 0xbfb8aa3b, v67
	v_exp_f32_e32 v76, v76
	v_exp_f32_e32 v77, v77
	v_add_f32_e32 v75, 1.0, v75
	v_rcp_f32_e32 v78, v75
	v_add_f32_e32 v75, 1.0, v76
	v_add_f32_e32 v76, 1.0, v77
	v_mul_f32_e32 v77, 0xbfb8aa3b, v72
	v_mul_f32_e32 v79, 0xbfb8aa3b, v68
	v_exp_f32_e32 v77, v77
	v_exp_f32_e32 v80, v79
	v_rcp_f32_e32 v79, v76
	v_mul_f32_e32 v74, 0xbfb8aa3b, v70
	v_add_f32_e32 v76, 1.0, v77
	v_add_f32_e32 v77, 1.0, v80
	v_mul_f32_e32 v80, 0xbfb8aa3b, v73
	v_exp_f32_e32 v81, v80
	v_mul_f32_e32 v80, 0xbfb8aa3b, v69
	v_exp_f32_e32 v74, v74
	v_exp_f32_e32 v82, v80
	v_rcp_f32_e32 v80, v77
	v_add_f32_e32 v77, 1.0, v81
	v_add_f32_e32 v74, 1.0, v74
	v_add_f32_e32 v81, 1.0, v82
	v_rcp_f32_e32 v74, v74
	v_rcp_f32_e32 v75, v75
	v_rcp_f32_e32 v76, v76
	v_rcp_f32_e32 v77, v77
	v_rcp_f32_e32 v81, v81
	s_cbranch_execnz .LBB0_370

.LBB0_370:
	v_cvt_pk_bf16_f32 v66, v74, v75
	v_cvt_pk_bf16_f32 v67, v76, v77
	v_cvt_pk_bf16_f32 v68, v78, v79
	v_cvt_pk_bf16_f32 v69, v80, v81
	s_and_b64 vcc, exec, s[14:15]
	s_cmp_lg_u64 s[6:7], 0
	s_cbranch_scc1 .Lwt_a9
	global_store_dwordx4 v[90:91], v[66:69], off offset:256 nt
	s_branch .Lwt_b9
.Lwt_a9:
	global_store_dwordx4 v[90:91], v[66:69], off offset:256 sc1 nt
.Lwt_b9:
	s_cbranch_vccz .LBB0_401
	s_nop 0
	v_mul_f32_e32 v67, 0xbfb8aa3b, v58
	v_exp_f32_e32 v67, v67
	v_mul_f32_e32 v68, 0xbfb8aa3b, v63
	v_mul_f32_e32 v69, 0xbfb8aa3b, v59
	v_exp_f32_e32 v68, v68
	v_exp_f32_e32 v69, v69
	v_add_f32_e32 v67, 1.0, v67
	v_rcp_f32_e32 v70, v67
	v_add_f32_e32 v67, 1.0, v68
	v_add_f32_e32 v68, 1.0, v69
	v_mul_f32_e32 v69, 0xbfb8aa3b, v64
	v_mul_f32_e32 v71, 0xbfb8aa3b, v60
	v_exp_f32_e32 v69, v69
	v_exp_f32_e32 v72, v71
	v_rcp_f32_e32 v71, v68
	v_mul_f32_e32 v66, 0xbfb8aa3b, v62
	v_add_f32_e32 v68, 1.0, v69
	v_add_f32_e32 v69, 1.0, v72
	v_mul_f32_e32 v72, 0xbfb8aa3b, v65
	v_exp_f32_e32 v73, v72
	v_mul_f32_e32 v72, 0xbfb8aa3b, v61
	v_exp_f32_e32 v66, v66
	v_exp_f32_e32 v74, v72
	v_rcp_f32_e32 v72, v69
	v_add_f32_e32 v69, 1.0, v73
	v_add_f32_e32 v66, 1.0, v66
	v_add_f32_e32 v73, 1.0, v74
	v_rcp_f32_e32 v66, v66
	v_rcp_f32_e32 v67, v67
	v_rcp_f32_e32 v68, v68
	v_rcp_f32_e32 v69, v69
	v_rcp_f32_e32 v73, v73
	s_cbranch_execnz .LBB0_373

.LBB0_373:
	v_add_u32_e32 v58, 0x80, v178
	v_mad_i64_i32 v[58:59], s[22:23], v58, s28, 0
	v_lshl_add_u64 v[58:59], v[58:59], 1, s[20:21]
	v_lshl_add_u64 v[74:75], v[156:157], 1, v[58:59]
	v_cvt_pk_bf16_f32 v58, v66, v67
	v_cvt_pk_bf16_f32 v59, v68, v69
	v_cvt_pk_bf16_f32 v60, v70, v71
	v_cvt_pk_bf16_f32 v61, v72, v73
	s_and_b64 vcc, exec, s[14:15]
	s_cmp_lg_u64 s[6:7], 0
	s_cbranch_scc1 .Lwt_a10
	global_store_dwordx4 v[74:75], v[58:61], off nt
	s_branch .Lwt_b10
.Lwt_a10:
	global_store_dwordx4 v[74:75], v[58:61], off sc1 nt
.Lwt_b10:
	s_cbranch_vccz .LBB0_402
	s_nop 0
	v_mul_f32_e32 v59, 0xbfb8aa3b, v50
	v_exp_f32_e32 v59, v59
	v_mul_f32_e32 v60, 0xbfb8aa3b, v55
	v_mul_f32_e32 v61, 0xbfb8aa3b, v51
	v_exp_f32_e32 v60, v60
	v_exp_f32_e32 v61, v61
	v_add_f32_e32 v59, 1.0, v59
	v_rcp_f32_e32 v62, v59
	v_add_f32_e32 v59, 1.0, v60
	v_add_f32_e32 v60, 1.0, v61
	v_mul_f32_e32 v61, 0xbfb8aa3b, v56
	v_mul_f32_e32 v63, 0xbfb8aa3b, v52
	v_exp_f32_e32 v61, v61
	v_exp_f32_e32 v64, v63
	v_rcp_f32_e32 v63, v60
	v_mul_f32_e32 v58, 0xbfb8aa3b, v54
	v_add_f32_e32 v60, 1.0, v61
	v_add_f32_e32 v61, 1.0, v64
	v_mul_f32_e32 v64, 0xbfb8aa3b, v57
	v_exp_f32_e32 v65, v64
	v_mul_f32_e32 v64, 0xbfb8aa3b, v53
	v_exp_f32_e32 v58, v58
	v_exp_f32_e32 v66, v64
	v_rcp_f32_e32 v64, v61
	v_add_f32_e32 v61, 1.0, v65
	v_add_f32_e32 v58, 1.0, v58
	v_add_f32_e32 v65, 1.0, v66
	v_rcp_f32_e32 v58, v58
	v_rcp_f32_e32 v59, v59
	v_rcp_f32_e32 v60, v60
	v_rcp_f32_e32 v61, v61
	v_rcp_f32_e32 v65, v65
	s_cbranch_execnz .LBB0_376

.LBB0_376:
	v_cvt_pk_bf16_f32 v50, v58, v59
	v_cvt_pk_bf16_f32 v51, v60, v61
	v_cvt_pk_bf16_f32 v52, v62, v63
	v_cvt_pk_bf16_f32 v53, v64, v65
	s_and_b64 vcc, exec, s[14:15]
	s_cmp_lg_u64 s[6:7], 0
	s_cbranch_scc1 .Lwt_a11
	global_store_dwordx4 v[74:75], v[50:53], off offset:256 nt
	s_branch .Lwt_b11
.Lwt_a11:
	global_store_dwordx4 v[74:75], v[50:53], off offset:256 sc1 nt
.Lwt_b11:
	s_cbranch_vccz .LBB0_403
	s_nop 0
	v_mul_f32_e32 v51, 0xbfb8aa3b, v42
	v_exp_f32_e32 v51, v51
	v_mul_f32_e32 v52, 0xbfb8aa3b, v47
	v_mul_f32_e32 v53, 0xbfb8aa3b, v43
	v_exp_f32_e32 v52, v52
	v_exp_f32_e32 v53, v53
	v_add_f32_e32 v51, 1.0, v51
	v_rcp_f32_e32 v54, v51
	v_add_f32_e32 v51, 1.0, v52
	v_add_f32_e32 v52, 1.0, v53
	v_mul_f32_e32 v53, 0xbfb8aa3b, v48
	v_mul_f32_e32 v55, 0xbfb8aa3b, v44
	v_exp_f32_e32 v53, v53
	v_exp_f32_e32 v56, v55
	v_rcp_f32_e32 v55, v52
	v_mul_f32_e32 v50, 0xbfb8aa3b, v46
	v_add_f32_e32 v52, 1.0, v53
	v_add_f32_e32 v53, 1.0, v56
	v_mul_f32_e32 v56, 0xbfb8aa3b, v49
	v_exp_f32_e32 v57, v56
	v_mul_f32_e32 v56, 0xbfb8aa3b, v45
	v_exp_f32_e32 v50, v50
	v_exp_f32_e32 v58, v56
	v_rcp_f32_e32 v56, v53
	v_add_f32_e32 v53, 1.0, v57
	v_add_f32_e32 v50, 1.0, v50
	v_add_f32_e32 v57, 1.0, v58
	v_rcp_f32_e32 v50, v50
	v_rcp_f32_e32 v51, v51
	v_rcp_f32_e32 v52, v52
	v_rcp_f32_e32 v53, v53
	v_rcp_f32_e32 v57, v57
	s_cbranch_execnz .LBB0_379

.LBB0_379:
	v_add_u32_e32 v42, 0x90, v178
	v_mad_i64_i32 v[42:43], s[22:23], v42, s28, 0
	v_lshl_add_u64 v[42:43], v[42:43], 1, s[20:21]
	v_lshl_add_u64 v[58:59], v[156:157], 1, v[42:43]
	v_cvt_pk_bf16_f32 v42, v50, v51
	v_cvt_pk_bf16_f32 v43, v52, v53
	v_cvt_pk_bf16_f32 v44, v54, v55
	v_cvt_pk_bf16_f32 v45, v56, v57
	s_and_b64 vcc, exec, s[14:15]
	s_cmp_lg_u64 s[6:7], 0
	s_cbranch_scc1 .Lwt_a12
	global_store_dwordx4 v[58:59], v[42:45], off nt
	s_branch .Lwt_b12
.Lwt_a12:
	global_store_dwordx4 v[58:59], v[42:45], off sc1 nt
.Lwt_b12:
	s_cbranch_vccz .LBB0_404
	s_nop 0
	v_mul_f32_e32 v43, 0xbfb8aa3b, v34
	v_exp_f32_e32 v43, v43
	v_mul_f32_e32 v44, 0xbfb8aa3b, v39
	v_mul_f32_e32 v45, 0xbfb8aa3b, v35
	v_exp_f32_e32 v44, v44
	v_exp_f32_e32 v45, v45
	v_add_f32_e32 v43, 1.0, v43
	v_rcp_f32_e32 v46, v43
	v_add_f32_e32 v43, 1.0, v44
	v_add_f32_e32 v44, 1.0, v45
	v_mul_f32_e32 v45, 0xbfb8aa3b, v40
	v_mul_f32_e32 v47, 0xbfb8aa3b, v36
	v_exp_f32_e32 v45, v45
	v_exp_f32_e32 v48, v47
	v_rcp_f32_e32 v47, v44
	v_mul_f32_e32 v42, 0xbfb8aa3b, v38
	v_add_f32_e32 v44, 1.0, v45
	v_add_f32_e32 v45, 1.0, v48
	v_mul_f32_e32 v48, 0xbfb8aa3b, v41
	v_exp_f32_e32 v49, v48
	v_mul_f32_e32 v48, 0xbfb8aa3b, v37
	v_exp_f32_e32 v42, v42
	v_exp_f32_e32 v50, v48
	v_rcp_f32_e32 v48, v45
	v_add_f32_e32 v45, 1.0, v49
	v_add_f32_e32 v42, 1.0, v42
	v_add_f32_e32 v49, 1.0, v50
	v_rcp_f32_e32 v42, v42
	v_rcp_f32_e32 v43, v43
	v_rcp_f32_e32 v44, v44
	v_rcp_f32_e32 v45, v45
	v_rcp_f32_e32 v49, v49
	s_cbranch_execnz .LBB0_382

.LBB0_382:
	v_cvt_pk_bf16_f32 v34, v42, v43
	v_cvt_pk_bf16_f32 v35, v44, v45
	v_cvt_pk_bf16_f32 v36, v46, v47
	v_cvt_pk_bf16_f32 v37, v48, v49
	s_and_b64 vcc, exec, s[14:15]
	s_cmp_lg_u64 s[6:7], 0
	s_cbranch_scc1 .Lwt_a13
	global_store_dwordx4 v[58:59], v[34:37], off offset:256 nt
	s_branch .Lwt_b13
.Lwt_a13:
	global_store_dwordx4 v[58:59], v[34:37], off offset:256 sc1 nt
.Lwt_b13:
	s_cbranch_vccz .LBB0_405
	s_nop 0
	v_mul_f32_e32 v35, 0xbfb8aa3b, v26
	v_exp_f32_e32 v35, v35
	v_mul_f32_e32 v36, 0xbfb8aa3b, v31
	v_mul_f32_e32 v37, 0xbfb8aa3b, v27
	v_exp_f32_e32 v36, v36
	v_exp_f32_e32 v37, v37
	v_add_f32_e32 v35, 1.0, v35
	v_rcp_f32_e32 v38, v35
	v_add_f32_e32 v35, 1.0, v36
	v_add_f32_e32 v36, 1.0, v37
	v_mul_f32_e32 v37, 0xbfb8aa3b, v32
	v_mul_f32_e32 v39, 0xbfb8aa3b, v28
	v_exp_f32_e32 v37, v37
	v_exp_f32_e32 v40, v39
	v_rcp_f32_e32 v39, v36
	v_mul_f32_e32 v34, 0xbfb8aa3b, v30
	v_add_f32_e32 v36, 1.0, v37
	v_add_f32_e32 v37, 1.0, v40
	v_mul_f32_e32 v40, 0xbfb8aa3b, v33
	v_exp_f32_e32 v41, v40
	v_mul_f32_e32 v40, 0xbfb8aa3b, v29
	v_exp_f32_e32 v34, v34
	v_exp_f32_e32 v42, v40
	v_rcp_f32_e32 v40, v37
	v_add_f32_e32 v37, 1.0, v41
	v_add_f32_e32 v34, 1.0, v34
	v_add_f32_e32 v41, 1.0, v42
	v_rcp_f32_e32 v34, v34
	v_rcp_f32_e32 v35, v35
	v_rcp_f32_e32 v36, v36
	v_rcp_f32_e32 v37, v37
	v_rcp_f32_e32 v41, v41
	s_cbranch_execnz .LBB0_385

.LBB0_385:
	v_add_u32_e32 v26, 0xa0, v178
	v_mad_i64_i32 v[26:27], s[22:23], v26, s28, 0
	v_lshl_add_u64 v[26:27], v[26:27], 1, s[20:21]
	v_lshl_add_u64 v[42:43], v[156:157], 1, v[26:27]
	v_cvt_pk_bf16_f32 v26, v34, v35
	v_cvt_pk_bf16_f32 v27, v36, v37
	v_cvt_pk_bf16_f32 v28, v38, v39
	v_cvt_pk_bf16_f32 v29, v40, v41
	s_and_b64 vcc, exec, s[14:15]
	s_cmp_lg_u64 s[6:7], 0
	s_cbranch_scc1 .Lwt_a14
	global_store_dwordx4 v[42:43], v[26:29], off nt
	s_branch .Lwt_b14
.Lwt_a14:
	global_store_dwordx4 v[42:43], v[26:29], off sc1 nt
.Lwt_b14:
	s_cbranch_vccz .LBB0_406
	s_nop 0
	v_mul_f32_e32 v27, 0xbfb8aa3b, v18
	v_exp_f32_e32 v27, v27
	v_mul_f32_e32 v28, 0xbfb8aa3b, v23
	v_mul_f32_e32 v29, 0xbfb8aa3b, v19
	v_exp_f32_e32 v28, v28
	v_exp_f32_e32 v29, v29
	v_add_f32_e32 v27, 1.0, v27
	v_rcp_f32_e32 v30, v27
	v_add_f32_e32 v27, 1.0, v28
	v_add_f32_e32 v28, 1.0, v29
	v_mul_f32_e32 v29, 0xbfb8aa3b, v24
	v_mul_f32_e32 v31, 0xbfb8aa3b, v20
	v_exp_f32_e32 v29, v29
	v_exp_f32_e32 v32, v31
	v_rcp_f32_e32 v31, v28
	v_mul_f32_e32 v26, 0xbfb8aa3b, v22
	v_add_f32_e32 v28, 1.0, v29
	v_add_f32_e32 v29, 1.0, v32
	v_mul_f32_e32 v32, 0xbfb8aa3b, v25
	v_exp_f32_e32 v33, v32
	v_mul_f32_e32 v32, 0xbfb8aa3b, v21
	v_exp_f32_e32 v26, v26
	v_exp_f32_e32 v34, v32
	v_rcp_f32_e32 v32, v29
	v_add_f32_e32 v29, 1.0, v33
	v_add_f32_e32 v26, 1.0, v26
	v_add_f32_e32 v33, 1.0, v34
	v_rcp_f32_e32 v26, v26
	v_rcp_f32_e32 v27, v27
	v_rcp_f32_e32 v28, v28
	v_rcp_f32_e32 v29, v29
	v_rcp_f32_e32 v33, v33
	s_cbranch_execnz .LBB0_388

.LBB0_388:
	v_cvt_pk_bf16_f32 v18, v26, v27
	v_cvt_pk_bf16_f32 v19, v28, v29
	v_cvt_pk_bf16_f32 v20, v30, v31
	v_cvt_pk_bf16_f32 v21, v32, v33
	s_and_b64 vcc, exec, s[14:15]
	s_cmp_lg_u64 s[6:7], 0
	s_cbranch_scc1 .Lwt_a15
	global_store_dwordx4 v[42:43], v[18:21], off offset:256 nt
	s_branch .Lwt_b15
.Lwt_a15:
	global_store_dwordx4 v[42:43], v[18:21], off offset:256 sc1 nt
.Lwt_b15:
	s_cbranch_vccz .LBB0_407
	s_nop 0
	v_mul_f32_e32 v19, 0xbfb8aa3b, v10
	v_exp_f32_e32 v19, v19
	v_mul_f32_e32 v20, 0xbfb8aa3b, v15
	v_mul_f32_e32 v21, 0xbfb8aa3b, v11
	v_exp_f32_e32 v20, v20
	v_exp_f32_e32 v21, v21
	v_add_f32_e32 v19, 1.0, v19
	v_rcp_f32_e32 v22, v19
	v_add_f32_e32 v19, 1.0, v20
	v_add_f32_e32 v20, 1.0, v21
	v_mul_f32_e32 v21, 0xbfb8aa3b, v16
	v_mul_f32_e32 v23, 0xbfb8aa3b, v12
	v_exp_f32_e32 v21, v21
	v_exp_f32_e32 v24, v23
	v_rcp_f32_e32 v23, v20
	v_mul_f32_e32 v18, 0xbfb8aa3b, v14
	v_add_f32_e32 v20, 1.0, v21
	v_add_f32_e32 v21, 1.0, v24
	v_mul_f32_e32 v24, 0xbfb8aa3b, v17
	v_exp_f32_e32 v25, v24
	v_mul_f32_e32 v24, 0xbfb8aa3b, v13
	v_exp_f32_e32 v18, v18
	v_exp_f32_e32 v26, v24
	v_rcp_f32_e32 v24, v21
	v_add_f32_e32 v21, 1.0, v25
	v_add_f32_e32 v18, 1.0, v18
	v_add_f32_e32 v25, 1.0, v26
	v_rcp_f32_e32 v18, v18
	v_rcp_f32_e32 v19, v19
	v_rcp_f32_e32 v20, v20
	v_rcp_f32_e32 v21, v21
	v_rcp_f32_e32 v25, v25
	s_cbranch_execnz .LBB0_391

.LBB0_391:
	v_add_u32_e32 v10, 0xb0, v178
	v_mad_i64_i32 v[10:11], s[22:23], v10, s28, 0
	v_lshl_add_u64 v[10:11], v[10:11], 1, s[20:21]
	v_lshl_add_u64 v[26:27], v[156:157], 1, v[10:11]
	v_cvt_pk_bf16_f32 v10, v18, v19
	v_cvt_pk_bf16_f32 v11, v20, v21
	v_cvt_pk_bf16_f32 v12, v22, v23
	v_cvt_pk_bf16_f32 v13, v24, v25
	s_and_b64 vcc, exec, s[14:15]
	s_cmp_lg_u64 s[6:7], 0
	s_cbranch_scc1 .Lwt_a16
	global_store_dwordx4 v[26:27], v[10:13], off nt
	s_branch .Lwt_b16
.Lwt_a16:
	global_store_dwordx4 v[26:27], v[10:13], off sc1 nt
.Lwt_b16:
	s_cbranch_vccz .LBB0_408
	s_nop 0
	v_mul_f32_e32 v11, 0xbfb8aa3b, v2
	v_exp_f32_e32 v11, v11
	v_mul_f32_e32 v12, 0xbfb8aa3b, v7
	v_mul_f32_e32 v13, 0xbfb8aa3b, v3
	v_exp_f32_e32 v12, v12
	v_exp_f32_e32 v13, v13
	v_add_f32_e32 v11, 1.0, v11
	v_rcp_f32_e32 v14, v11
	v_add_f32_e32 v11, 1.0, v12
	v_add_f32_e32 v12, 1.0, v13
	v_mul_f32_e32 v13, 0xbfb8aa3b, v8
	v_mul_f32_e32 v15, 0xbfb8aa3b, v4
	v_exp_f32_e32 v13, v13
	v_exp_f32_e32 v16, v15
	v_rcp_f32_e32 v15, v12
	v_mul_f32_e32 v10, 0xbfb8aa3b, v6
	v_add_f32_e32 v12, 1.0, v13
	v_add_f32_e32 v13, 1.0, v16
	v_mul_f32_e32 v16, 0xbfb8aa3b, v9
	v_exp_f32_e32 v17, v16
	v_mul_f32_e32 v16, 0xbfb8aa3b, v5
	v_exp_f32_e32 v10, v10
	v_exp_f32_e32 v18, v16
	v_rcp_f32_e32 v16, v13
	v_add_f32_e32 v13, 1.0, v17
	v_add_f32_e32 v10, 1.0, v10
	v_add_f32_e32 v17, 1.0, v18
	v_rcp_f32_e32 v10, v10
	v_rcp_f32_e32 v11, v11
	v_rcp_f32_e32 v12, v12
	v_rcp_f32_e32 v13, v13
	v_rcp_f32_e32 v17, v17
	s_cbranch_execnz .LBB0_337
	s_branch .LBB0_409
